# phase-0 prep reads the once-used f32 inputs with the nt cache policy
# baseline (speedup 1.0000x reference)
.LBB0_382:
	s_or_saveexec_b64 s[8:9], s[8:9]
	s_lshl_b32 s1, s22, 10
	s_sub_i32 s24, 0, s1
	v_mov_b32_e32 v7, 0
	v_mov_b32_e32 v6, 0
	v_mov_b32_e32 v5, 0
	v_mov_b32_e32 v4, 0
	s_xor_b64 exec, exec, s[8:9]
	s_cbranch_execz .LBB0_387
	v_ashrrev_i32_e32 v9, 31, v8
	s_add_i32 s1, s24, s16
	v_lshl_add_u64 v[6:7], v[8:9], 2, s[46:47]
	v_add_u32_e32 v10, s1, v16
	s_movk_i32 s1, 0x3080
	v_mad_i64_i32 v[4:5], s[22:23], v10, s1, v[6:7]
	global_load_dwordx4 v[22:25], v[4:5], off nt
	s_movk_i32 s1, 0x200
	v_cmp_gt_i32_e32 vcc, s1, v8
	v_cndmask_b32_e64 v5, 0, 1, s[6:7]
	v_ashrrev_i32_e32 v11, 31, v10
	v_cndmask_b32_e32 v4, 1.0, v215, vcc
	v_cmp_ne_u32_e64 s[40:41], 1, v5
	s_andn2_b64 vcc, exec, s[6:7]
	v_lshl_add_u64 v[8:9], v[10:11], 2, s[44:45]
	s_waitcnt vmcnt(0)
	v_pk_mul_f32 v[12:13], v[4:5], v[24:25] op_sel_hi:[0,1]
	v_pk_mul_f32 v[14:15], v[4:5], v[22:23] op_sel_hi:[0,1]
	s_cbranch_vccnz .LBB0_385
	global_load_dword v22, v[8:9], off
	s_waitcnt vmcnt(0)
	v_pk_mul_f32 v[12:13], v[12:13], v[22:23] op_sel_hi:[1,0]
	v_pk_mul_f32 v[14:15], v[14:15], v[22:23] op_sel_hi:[1,0]
.LBB0_385:
	v_add_u32_e32 v5, 32, v10
	s_movk_i32 s1, 0x3080
	v_mad_i64_i32 v[6:7], s[22:23], v5, s1, v[6:7]
	global_load_dwordx4 v[22:25], v[6:7], off nt
	v_mov_b32_e32 v5, v4
	v_mov_b32_e32 v6, v4
	v_mov_b32_e32 v7, v4
	s_and_b64 vcc, exec, s[40:41]
	ds_write2_b32 v0, v14, v15 offset1:1
	ds_write2_b32 v0, v12, v13 offset0:2 offset1:3
	s_waitcnt vmcnt(0)
	v_pk_mul_f32 v[6:7], v[6:7], v[24:25]
	v_pk_mul_f32 v[4:5], v[4:5], v[22:23]
	s_cbranch_vccnz .LBB0_387
	global_load_dword v8, v[8:9], off offset:128
	s_waitcnt vmcnt(0)
	v_pk_mul_f32 v[6:7], v[6:7], v[8:9] op_sel_hi:[1,0]
	v_pk_mul_f32 v[4:5], v[4:5], v[8:9] op_sel_hi:[1,0]

.LBB0_390:
	s_or_saveexec_b64 s[22:23], s[22:23]
	v_mov_b32_e32 v7, 0
	v_mov_b32_e32 v6, 0
	v_mov_b32_e32 v5, 0
	v_mov_b32_e32 v4, 0
	s_xor_b64 exec, exec, s[22:23]
	s_cbranch_execz .LBB0_395
	s_and_b32 s1, s26, 0x3fffff0
	s_sub_i32 s1, s25, s1
	s_lshl_b32 s26, s1, 6
	v_ashrrev_i32_e32 v9, 31, v8
	v_lshl_add_u64 v[6:7], v[8:9], 2, s[46:47]
	v_add_u32_e32 v26, s26, v16
	s_movk_i32 s1, 0x3080
	v_mad_i64_i32 v[4:5], s[28:29], v26, s1, v[6:7]
	global_load_dwordx4 v[22:25], v[4:5], off nt
	s_movk_i32 s1, 0x200
	v_cmp_gt_i32_e32 vcc, s1, v8
	v_cndmask_b32_e64 v5, 0, 1, s[6:7]
	v_ashrrev_i32_e32 v27, 31, v26
	v_cndmask_b32_e32 v4, 1.0, v215, vcc
	v_cmp_ne_u32_e64 s[40:41], 1, v5
	s_andn2_b64 vcc, exec, s[6:7]
	v_lshl_add_u64 v[8:9], v[26:27], 2, s[44:45]
	s_waitcnt vmcnt(0)
	v_pk_mul_f32 v[10:11], v[4:5], v[24:25] op_sel_hi:[0,1]
	v_pk_mul_f32 v[12:13], v[4:5], v[22:23] op_sel_hi:[0,1]
	s_cbranch_vccnz .LBB0_393
	global_load_dword v22, v[8:9], off
	s_waitcnt vmcnt(0)
	v_pk_mul_f32 v[10:11], v[10:11], v[22:23] op_sel_hi:[1,0]
	v_pk_mul_f32 v[12:13], v[12:13], v[22:23] op_sel_hi:[1,0]
.LBB0_393:
	v_add_u32_e32 v5, s26, v19
	s_movk_i32 s1, 0x3080
	v_mad_i64_i32 v[6:7], s[26:27], v5, s1, v[6:7]
	global_load_dwordx4 v[22:25], v[6:7], off nt
	v_mov_b32_e32 v5, v4
	v_mov_b32_e32 v6, v4
	v_mov_b32_e32 v7, v4
	s_and_b64 vcc, exec, s[40:41]
	ds_write2_b32 v14, v12, v13 offset1:1
	ds_write2_b32 v15, v10, v11 offset1:1
	s_waitcnt vmcnt(0)
	v_pk_mul_f32 v[6:7], v[6:7], v[24:25]
	v_pk_mul_f32 v[4:5], v[4:5], v[22:23]
	s_cbranch_vccnz .LBB0_395
	global_load_dword v8, v[8:9], off offset:128
	s_waitcnt vmcnt(0)
	v_pk_mul_f32 v[6:7], v[6:7], v[8:9] op_sel_hi:[1,0]
	v_pk_mul_f32 v[4:5], v[4:5], v[8:9] op_sel_hi:[1,0]

.LBB0_398:
	s_or_saveexec_b64 s[22:23], s[22:23]
	v_mov_b32_e32 v7, 0
	v_mov_b32_e32 v6, 0
	v_mov_b32_e32 v5, 0
	v_mov_b32_e32 v4, 0
	s_xor_b64 exec, exec, s[22:23]
	s_cbranch_execz .LBB0_403
	s_lshl_b32 s1, s27, 4
	s_sub_i32 s1, s26, s1
	s_lshl_b32 s26, s1, 6
	v_ashrrev_i32_e32 v9, 31, v8
	v_lshl_add_u64 v[6:7], v[8:9], 2, s[46:47]
	v_add_u32_e32 v26, s26, v16
	s_movk_i32 s1, 0x3080
	v_mad_i64_i32 v[4:5], s[28:29], v26, s1, v[6:7]
	global_load_dwordx4 v[22:25], v[4:5], off nt
	s_movk_i32 s1, 0x200
	v_cmp_gt_i32_e32 vcc, s1, v8
	v_cndmask_b32_e64 v5, 0, 1, s[6:7]
	v_ashrrev_i32_e32 v27, 31, v26
	v_cndmask_b32_e32 v4, 1.0, v215, vcc
	v_cmp_ne_u32_e64 s[40:41], 1, v5
	s_andn2_b64 vcc, exec, s[6:7]
	v_lshl_add_u64 v[8:9], v[26:27], 2, s[44:45]
	s_waitcnt vmcnt(0)
	v_pk_mul_f32 v[10:11], v[4:5], v[24:25] op_sel_hi:[0,1]
	v_pk_mul_f32 v[12:13], v[4:5], v[22:23] op_sel_hi:[0,1]
	s_cbranch_vccnz .LBB0_401
	global_load_dword v22, v[8:9], off
	s_waitcnt vmcnt(0)
	v_pk_mul_f32 v[10:11], v[10:11], v[22:23] op_sel_hi:[1,0]
	v_pk_mul_f32 v[12:13], v[12:13], v[22:23] op_sel_hi:[1,0]

.LBB0_419:
	s_ashr_i32 s1, s17, 31
	s_lshr_b32 s1, s1, 28
	s_add_i32 s1, s17, s1
	s_ashr_i32 s1, s1, 4
	s_lshl_b32 s24, s1, 10
	s_lshl_b32 s20, s1, 6
	s_sub_i32 s1, s16, s24
	v_or_b32_e32 v10, s20, v3
	v_add_u32_e32 v16, s1, v4
	v_ashrrev_i32_e32 v11, 31, v10
	v_ashrrev_i32_e32 v17, 31, v16
	s_waitcnt lgkmcnt(0)
	v_lshl_add_u64 v[14:15], v[10:11], 2, s[6:7]
	v_lshlrev_b64 v[10:11], 12, v[16:17]
	v_add_u32_e32 v16, 32, v16
	v_lshl_add_u64 v[10:11], v[14:15], 0, v[10:11]
	v_ashrrev_i32_e32 v17, 31, v16
	global_load_dwordx4 v[10:13], v[10:11], off nt
	v_lshlrev_b64 v[16:17], 12, v[16:17]
	v_lshl_add_u64 v[14:15], v[14:15], 0, v[16:17]
	global_load_dwordx4 v[14:17], v[14:15], off nt
	s_mul_i32 s25, s4, 0x10400
	s_add_i32 s21, s14, s17
	v_add_u32_e32 v0, s25, v8
	s_cmpk_lt_i32 s21, 0x100
	v_add_u32_e32 v0, v0, v6
	s_cselect_b64 s[22:23], -1, 0
	s_cmpk_gt_i32 s21, 0xff
	v_add_u32_e32 v18, 0x2080, v0
	v_add_u32_e32 v19, 0x2088, v0
	s_waitcnt vmcnt(1)
	ds_write2_b32 v0, v10, v11 offset1:1
	ds_write2_b32 v0, v12, v13 offset0:2 offset1:3
	s_waitcnt vmcnt(0)
	ds_write2_b32 v18, v14, v15 offset1:1
	ds_write2_b32 v19, v16, v17 offset1:1
	s_cbranch_scc1 .LBB0_423
	s_ashr_i32 s1, s21, 31
	s_lshr_b32 s1, s1, 28
	s_add_i32 s1, s21, s1
	s_lshl_b32 s26, s1, 2
	s_andn2_b32 s26, s26, 63
	s_and_b32 s1, s1, 0x3fffff0
	s_sub_i32 s1, s21, s1
	v_or_b32_e32 v10, s26, v3
	s_lshl_b32 s1, s1, 6
	v_ashrrev_i32_e32 v11, 31, v10
	v_lshl_add_u64 v[14:15], v[10:11], 2, s[6:7]
	v_add_u32_e32 v10, s1, v4
	v_ashrrev_i32_e32 v11, 31, v10
	v_lshlrev_b64 v[10:11], 12, v[10:11]
	v_add_u32_e32 v16, s1, v7
	v_lshl_add_u64 v[10:11], v[14:15], 0, v[10:11]
	v_ashrrev_i32_e32 v17, 31, v16
	global_load_dwordx4 v[10:13], v[10:11], off nt
	v_lshlrev_b64 v[16:17], 12, v[16:17]
	v_lshl_add_u64 v[14:15], v[14:15], 0, v[16:17]
	global_load_dwordx4 v[14:17], v[14:15], off nt
	s_add_i32 s26, s18, s17
	v_add_u32_e32 v18, 0x4100, v0
	s_cmpk_gt_i32 s26, 0xff
	v_add_u32_e32 v19, 0x4108, v0
	v_add_u32_e32 v20, 0x6180, v0
	v_add_u32_e32 v21, 0x6188, v0
	s_waitcnt vmcnt(1)
	ds_write2_b32 v18, v10, v11 offset1:1
	ds_write2_b32 v19, v12, v13 offset1:1
	s_waitcnt vmcnt(0)
	ds_write2_b32 v20, v14, v15 offset1:1
	ds_write2_b32 v21, v16, v17 offset1:1
	s_cbranch_scc1 .LBB0_423
	s_ashr_i32 s1, s26, 31
	s_lshr_b32 s1, s1, 28
	s_add_i32 s1, s26, s1
	s_lshl_b32 s27, s1, 2
	s_andn2_b32 s27, s27, 63
	s_and_b32 s1, s1, 0x3fffff0
	s_sub_i32 s1, s26, s1
	v_or_b32_e32 v10, s27, v3
	s_lshl_b32 s1, s1, 6
	v_ashrrev_i32_e32 v11, 31, v10
	v_lshl_add_u64 v[14:15], v[10:11], 2, s[6:7]
	v_add_u32_e32 v10, s1, v4
	v_ashrrev_i32_e32 v11, 31, v10
	v_lshlrev_b64 v[10:11], 12, v[10:11]
	v_add_u32_e32 v16, s1, v7
	v_lshl_add_u64 v[10:11], v[14:15], 0, v[10:11]
	v_ashrrev_i32_e32 v17, 31, v16
	global_load_dwordx4 v[10:13], v[10:11], off nt
	v_lshlrev_b64 v[16:17], 12, v[16:17]
	v_lshl_add_u64 v[14:15], v[14:15], 0, v[16:17]
	global_load_dwordx4 v[14:17], v[14:15], off nt
	s_add_i32 s26, s15, s17
	v_add_u32_e32 v18, 0x8200, v0
	s_cmpk_gt_i32 s26, 0xff
	v_add_u32_e32 v19, 0x8208, v0
	v_add_u32_e32 v20, 0xa280, v0
	v_add_u32_e32 v21, 0xa288, v0
	s_waitcnt vmcnt(1)
	ds_write2_b32 v18, v10, v11 offset1:1
	ds_write2_b32 v19, v12, v13 offset1:1
	s_waitcnt vmcnt(0)
	ds_write2_b32 v20, v14, v15 offset1:1
	ds_write2_b32 v21, v16, v17 offset1:1
	s_cbranch_scc1 .LBB0_423
	s_ashr_i32 s1, s26, 31
	s_lshr_b32 s1, s1, 28
	s_add_i32 s1, s26, s1
	s_lshl_b32 s27, s1, 2
	s_andn2_b32 s27, s27, 63
	s_and_b32 s1, s1, 0x3fffff0
	s_sub_i32 s1, s26, s1
	v_or_b32_e32 v10, s27, v3
	s_lshl_b32 s1, s1, 6
	v_ashrrev_i32_e32 v11, 31, v10
	v_lshl_add_u64 v[14:15], v[10:11], 2, s[6:7]
	v_add_u32_e32 v10, s1, v4
	v_ashrrev_i32_e32 v11, 31, v10
	v_lshlrev_b64 v[10:11], 12, v[10:11]
	v_add_u32_e32 v16, s1, v7
	v_lshl_add_u64 v[10:11], v[14:15], 0, v[10:11]
	v_ashrrev_i32_e32 v17, 31, v16
	global_load_dwordx4 v[10:13], v[10:11], off nt
	v_lshlrev_b64 v[16:17], 12, v[16:17]
	v_lshl_add_u64 v[14:15], v[14:15], 0, v[16:17]
	global_load_dwordx4 v[14:17], v[14:15], off nt
	v_add_u32_e32 v18, 0xc300, v0
	v_add_u32_e32 v19, 0xc308, v0
	v_add_u32_e32 v20, 0xe380, v0
	v_add_u32_e32 v0, 0xe388, v0
	s_waitcnt vmcnt(1)
	ds_write2_b32 v18, v10, v11 offset1:1
	ds_write2_b32 v19, v12, v13 offset1:1
	s_waitcnt vmcnt(0)
	ds_write2_b32 v20, v14, v15 offset1:1
	ds_write2_b32 v0, v16, v17 offset1:1

.LBB0_430:
	s_ashr_i32 s1, s17, 31
	s_lshr_b32 s1, s1, 28
	s_add_i32 s1, s17, s1
	s_ashr_i32 s24, s1, 4
	s_lshl_b32 s22, s24, 10
	s_ashr_i32 s1, s1, 8
	s_sub_i32 s26, 0, s22
	s_mul_hi_i32 s22, s1, 0x55555556
	s_lshr_b32 s23, s22, 31
	s_add_i32 s22, s22, s23
	s_mul_i32 s21, s4, 0x10400
	s_mul_i32 s22, s22, 3
	s_add_i32 s27, s21, 0
	s_lshl_b32 s20, s24, 6
	s_sub_i32 s1, s1, s22
	s_cmp_lt_i32 s1, 2
	s_cselect_b64 s[22:23], -1, 0
	s_bitcmp0_b32 s24, 0
	s_cselect_b64 s[24:25], -1, 0
	s_and_b64 s[24:25], s[24:25], s[22:23]
	s_mov_b64 s[22:23], -1
	s_and_b64 vcc, exec, s[24:25]
	s_cbranch_vccnz .LBB0_432
	s_add_i32 s1, s26, s16
	v_add_u32_e32 v26, s1, v4
	v_or_b32_e32 v20, s20, v3
	v_ashrrev_i32_e32 v27, 31, v26
	v_ashrrev_i32_e32 v21, 31, v20
	v_lshl_add_u64 v[28:29], v[26:27], 2, s[8:9]
	s_waitcnt lgkmcnt(0)
	v_lshl_add_u64 v[24:25], v[20:21], 2, s[6:7]
	s_mov_b32 s1, 0x9000
	global_load_dword v0, v[28:29], off
	v_add_u32_e32 v28, 32, v26
	v_mad_i64_i32 v[20:21], s[22:23], v26, s1, v[24:25]
	v_ashrrev_i32_e32 v29, 31, v28
	global_load_dwordx4 v[20:23], v[20:21], off nt
	v_mad_i64_i32 v[24:25], s[22:23], v28, s1, v[24:25]
	v_lshl_add_u64 v[28:29], v[28:29], 2, s[8:9]
	global_load_dwordx4 v[24:27], v[24:25], off nt
	s_mov_b64 s[22:23], 0
	global_load_dword v28, v[28:29], off
	v_lshlrev_b32_e32 v29, 2, v3
	v_add3_u32 v29, s27, v29, v9
	v_add_u32_e32 v30, 0x2080, v29
	v_add_u32_e32 v31, 0x2088, v29
	s_waitcnt vmcnt(2)
	v_pk_mul_f32 v[22:23], v[22:23], v[0:1] op_sel_hi:[1,0]
	v_pk_mul_f32 v[20:21], v[20:21], v[0:1] op_sel_hi:[1,0]
	ds_write2_b32 v29, v20, v21 offset1:1
	ds_write2_b32 v29, v22, v23 offset0:2 offset1:3
	s_waitcnt vmcnt(0)
	v_pk_mul_f32 v[22:23], v[24:25], v[28:29] op_sel_hi:[1,0]
	v_pk_mul_f32 v[20:21], v[26:27], v[28:29] op_sel_hi:[1,0]
	ds_write2_b32 v30, v22, v23 offset1:1
	ds_write2_b32 v31, v20, v21 offset1:1

.LBB0_438:
	v_or_b32_e32 v20, s30, v3
	v_ashrrev_i32_e32 v21, 31, v20
	v_add_u32_e32 v26, s29, v4
	s_waitcnt lgkmcnt(0)
	v_lshl_add_u64 v[24:25], v[20:21], 2, s[6:7]
	v_ashrrev_i32_e32 v27, 31, v26
	s_mov_b32 s1, 0x9000
	v_mad_i64_i32 v[20:21], s[24:25], v26, s1, v[24:25]
	v_lshl_add_u64 v[26:27], v[26:27], 2, s[8:9]
	global_load_dword v0, v[26:27], off
	v_add_u32_e32 v26, s29, v10
	v_ashrrev_i32_e32 v27, 31, v26
	global_load_dwordx4 v[20:23], v[20:21], off nt
	v_mad_i64_i32 v[24:25], s[24:25], v26, s1, v[24:25]
	v_lshl_add_u64 v[26:27], v[26:27], 2, s[8:9]
	global_load_dword v28, v[26:27], off
	s_nop 0
	global_load_dwordx4 v[24:27], v[24:25], off nt
	v_lshlrev_b32_e32 v29, 2, v3
	v_add3_u32 v29, s27, v29, v9
	v_add_u32_e32 v30, 0x4100, v29
	v_add_u32_e32 v31, 0x4108, v29
	v_add_u32_e32 v32, 0x6180, v29
	v_add_u32_e32 v29, 0x6188, v29
	s_waitcnt vmcnt(2)
	v_pk_mul_f32 v[20:21], v[20:21], v[0:1] op_sel_hi:[1,0]
	v_pk_mul_f32 v[22:23], v[22:23], v[0:1] op_sel_hi:[1,0]
	s_waitcnt vmcnt(0)
	v_pk_mul_f32 v[26:27], v[26:27], v[28:29] op_sel_hi:[1,0]
	v_pk_mul_f32 v[24:25], v[24:25], v[28:29] op_sel_hi:[1,0]
	ds_write2_b32 v30, v20, v21 offset1:1
	ds_write2_b32 v31, v22, v23 offset1:1
	ds_write2_b32 v32, v24, v25 offset1:1
	ds_write2_b32 v29, v26, v27 offset1:1
	s_cbranch_execnz .LBB0_437

.LBB0_443:
	v_or_b32_e32 v20, s30, v3
	v_ashrrev_i32_e32 v21, 31, v20
	v_add_u32_e32 v26, s29, v4
	s_waitcnt lgkmcnt(0)
	v_lshl_add_u64 v[24:25], v[20:21], 2, s[6:7]
	v_ashrrev_i32_e32 v27, 31, v26
	s_mov_b32 s1, 0x9000
	v_mad_i64_i32 v[20:21], s[24:25], v26, s1, v[24:25]
	v_lshl_add_u64 v[26:27], v[26:27], 2, s[8:9]
	global_load_dword v0, v[26:27], off
	v_add_u32_e32 v26, s29, v10
	v_ashrrev_i32_e32 v27, 31, v26
	global_load_dwordx4 v[20:23], v[20:21], off nt
	v_mad_i64_i32 v[24:25], s[24:25], v26, s1, v[24:25]
	v_lshl_add_u64 v[26:27], v[26:27], 2, s[8:9]
	global_load_dword v28, v[26:27], off
	s_nop 0
	global_load_dwordx4 v[24:27], v[24:25], off nt
	v_lshlrev_b32_e32 v29, 2, v3
	v_add3_u32 v29, s27, v29, v9
	v_add_u32_e32 v30, 0x8200, v29
	v_add_u32_e32 v31, 0x8208, v29
	v_add_u32_e32 v32, 0xa280, v29
	v_add_u32_e32 v29, 0xa288, v29
	s_waitcnt vmcnt(2)
	v_pk_mul_f32 v[20:21], v[20:21], v[0:1] op_sel_hi:[1,0]
	v_pk_mul_f32 v[22:23], v[22:23], v[0:1] op_sel_hi:[1,0]
	s_waitcnt vmcnt(0)
	v_pk_mul_f32 v[26:27], v[26:27], v[28:29] op_sel_hi:[1,0]
	v_pk_mul_f32 v[24:25], v[24:25], v[28:29] op_sel_hi:[1,0]
	ds_write2_b32 v30, v20, v21 offset1:1
	ds_write2_b32 v31, v22, v23 offset1:1
	ds_write2_b32 v32, v24, v25 offset1:1
	ds_write2_b32 v29, v26, v27 offset1:1
	s_cbranch_execnz .LBB0_442

.LBB0_445:
	s_ashr_i32 s1, s24, 31
	s_lshr_b32 s1, s1, 28
	s_add_i32 s1, s24, s1
	s_and_b32 s25, s1, 0x3fffff0
	s_ashr_i32 s31, s1, 4
	s_sub_i32 s24, s24, s25
	s_ashr_i32 s1, s1, 8
	s_lshl_b32 s29, s24, 6
	s_mul_hi_i32 s24, s1, 0x55555556
	s_lshr_b32 s25, s24, 31
	s_add_i32 s24, s24, s25
	s_mul_i32 s24, s24, 3
	s_lshl_b32 s30, s31, 6
	s_sub_i32 s1, s1, s24
	s_cmp_lt_i32 s1, 2
	s_cselect_b64 s[24:25], -1, 0
	s_bitcmp0_b32 s31, 0
	s_cselect_b64 s[36:37], -1, 0
	s_and_b64 s[36:37], s[36:37], s[24:25]
	s_mov_b64 s[24:25], -1
	s_and_b64 vcc, exec, s[36:37]
	s_cbranch_vccnz .LBB0_447
	v_or_b32_e32 v20, s30, v3
	v_ashrrev_i32_e32 v21, 31, v20
	v_add_u32_e32 v26, s29, v4
	s_waitcnt lgkmcnt(0)
	v_lshl_add_u64 v[24:25], v[20:21], 2, s[6:7]
	v_ashrrev_i32_e32 v27, 31, v26
	s_mov_b32 s1, 0x9000
	v_mad_i64_i32 v[20:21], s[24:25], v26, s1, v[24:25]
	v_lshl_add_u64 v[26:27], v[26:27], 2, s[8:9]
	global_load_dword v0, v[26:27], off
	v_add_u32_e32 v26, s29, v10
	v_ashrrev_i32_e32 v27, 31, v26
	global_load_dwordx4 v[20:23], v[20:21], off nt
	v_mad_i64_i32 v[24:25], s[24:25], v26, s1, v[24:25]
	v_lshl_add_u64 v[26:27], v[26:27], 2, s[8:9]
	global_load_dword v28, v[26:27], off
	s_nop 0
	global_load_dwordx4 v[24:27], v[24:25], off nt
	v_lshlrev_b32_e32 v29, 2, v3
	v_add3_u32 v29, s27, v29, v9
	v_add_u32_e32 v30, 0xc300, v29
	v_add_u32_e32 v31, 0xc308, v29
	v_add_u32_e32 v32, 0xe380, v29
	v_add_u32_e32 v29, 0xe388, v29
	s_mov_b64 s[24:25], 0
	s_waitcnt vmcnt(2)
	v_pk_mul_f32 v[20:21], v[20:21], v[0:1] op_sel_hi:[1,0]
	v_pk_mul_f32 v[22:23], v[22:23], v[0:1] op_sel_hi:[1,0]
	s_waitcnt vmcnt(0)
	v_pk_mul_f32 v[26:27], v[26:27], v[28:29] op_sel_hi:[1,0]
	v_pk_mul_f32 v[24:25], v[24:25], v[28:29] op_sel_hi:[1,0]
	ds_write2_b32 v30, v20, v21 offset1:1
	ds_write2_b32 v31, v22, v23 offset1:1
	ds_write2_b32 v32, v24, v25 offset1:1
	ds_write2_b32 v29, v26, v27 offset1:1

.LBB0_457:
	s_ashr_i32 s1, s21, 31
	s_lshr_b32 s1, s1, 28
	s_add_i32 s1, s21, s1
	s_ashr_i32 s1, s1, 4
	s_lshl_b32 s24, s1, 10
	s_lshl_b32 s22, s1, 6
	s_sub_i32 s1, s20, s24
	v_or_b32_e32 v10, s22, v3
	v_add_u32_e32 v16, s1, v4
	v_ashrrev_i32_e32 v11, 31, v10
	v_ashrrev_i32_e32 v17, 31, v16
	s_waitcnt lgkmcnt(0)
	v_lshl_add_u64 v[14:15], v[10:11], 2, s[6:7]
	v_lshlrev_b64 v[10:11], 12, v[16:17]
	v_add_u32_e32 v16, 32, v16
	v_lshl_add_u64 v[10:11], v[14:15], 0, v[10:11]
	v_ashrrev_i32_e32 v17, 31, v16
	global_load_dwordx4 v[10:13], v[10:11], off nt
	v_lshlrev_b64 v[16:17], 12, v[16:17]
	v_lshl_add_u64 v[14:15], v[14:15], 0, v[16:17]
	global_load_dwordx4 v[14:17], v[14:15], off nt
	s_mul_i32 s25, s4, 0x10400
	s_add_i32 s23, s14, s21
	v_add_u32_e32 v0, s25, v8
	s_cmpk_lt_i32 s23, 0x100
	v_add_u32_e32 v0, v0, v6
	s_cselect_b64 s[16:17], -1, 0
	s_cmpk_gt_i32 s23, 0xff
	v_add_u32_e32 v18, 0x2080, v0
	v_add_u32_e32 v19, 0x2088, v0
	s_waitcnt vmcnt(1)
	ds_write2_b32 v0, v10, v11 offset1:1
	ds_write2_b32 v0, v12, v13 offset0:2 offset1:3
	s_waitcnt vmcnt(0)
	ds_write2_b32 v18, v14, v15 offset1:1
	ds_write2_b32 v19, v16, v17 offset1:1
	s_cbranch_scc1 .LBB0_461
	s_ashr_i32 s1, s23, 31
	s_lshr_b32 s1, s1, 28
	s_add_i32 s1, s23, s1
	s_lshl_b32 s26, s1, 2
	s_andn2_b32 s26, s26, 63
	s_and_b32 s1, s1, 0x3fffff0
	s_sub_i32 s1, s23, s1
	v_or_b32_e32 v10, s26, v3
	s_lshl_b32 s1, s1, 6
	v_ashrrev_i32_e32 v11, 31, v10
	v_lshl_add_u64 v[14:15], v[10:11], 2, s[6:7]
	v_add_u32_e32 v10, s1, v4
	v_ashrrev_i32_e32 v11, 31, v10
	v_lshlrev_b64 v[10:11], 12, v[10:11]
	v_add_u32_e32 v16, s1, v7
	v_lshl_add_u64 v[10:11], v[14:15], 0, v[10:11]
	v_ashrrev_i32_e32 v17, 31, v16
	global_load_dwordx4 v[10:13], v[10:11], off nt
	v_lshlrev_b64 v[16:17], 12, v[16:17]
	v_lshl_add_u64 v[14:15], v[14:15], 0, v[16:17]
	global_load_dwordx4 v[14:17], v[14:15], off nt
	s_add_i32 s26, s18, s21
	v_add_u32_e32 v18, 0x4100, v0
	s_cmpk_gt_i32 s26, 0xff
	v_add_u32_e32 v19, 0x4108, v0
	v_add_u32_e32 v20, 0x6180, v0
	v_add_u32_e32 v21, 0x6188, v0
	s_waitcnt vmcnt(1)
	ds_write2_b32 v18, v10, v11 offset1:1
	ds_write2_b32 v19, v12, v13 offset1:1
	s_waitcnt vmcnt(0)
	ds_write2_b32 v20, v14, v15 offset1:1
	ds_write2_b32 v21, v16, v17 offset1:1
	s_cbranch_scc1 .LBB0_461
	s_ashr_i32 s1, s26, 31
	s_lshr_b32 s1, s1, 28
	s_add_i32 s1, s26, s1
	s_lshl_b32 s27, s1, 2
	s_andn2_b32 s27, s27, 63
	s_and_b32 s1, s1, 0x3fffff0
	s_sub_i32 s1, s26, s1
	v_or_b32_e32 v10, s27, v3
	s_lshl_b32 s1, s1, 6
	v_ashrrev_i32_e32 v11, 31, v10
	v_lshl_add_u64 v[14:15], v[10:11], 2, s[6:7]
	v_add_u32_e32 v10, s1, v4
	v_ashrrev_i32_e32 v11, 31, v10
	v_lshlrev_b64 v[10:11], 12, v[10:11]
	v_add_u32_e32 v16, s1, v7
	v_lshl_add_u64 v[10:11], v[14:15], 0, v[10:11]
	v_ashrrev_i32_e32 v17, 31, v16
	global_load_dwordx4 v[10:13], v[10:11], off nt
	v_lshlrev_b64 v[16:17], 12, v[16:17]
	v_lshl_add_u64 v[14:15], v[14:15], 0, v[16:17]
	global_load_dwordx4 v[14:17], v[14:15], off nt
	s_add_i32 s26, s15, s21
	v_add_u32_e32 v18, 0x8200, v0
	s_cmpk_gt_i32 s26, 0xff
	v_add_u32_e32 v19, 0x8208, v0
	v_add_u32_e32 v20, 0xa280, v0
	v_add_u32_e32 v21, 0xa288, v0
	s_waitcnt vmcnt(1)
	ds_write2_b32 v18, v10, v11 offset1:1
	ds_write2_b32 v19, v12, v13 offset1:1
	s_waitcnt vmcnt(0)
	ds_write2_b32 v20, v14, v15 offset1:1
	ds_write2_b32 v21, v16, v17 offset1:1
	s_cbranch_scc1 .LBB0_461
	s_ashr_i32 s1, s26, 31
	s_lshr_b32 s1, s1, 28
	s_add_i32 s1, s26, s1
	s_lshl_b32 s27, s1, 2
	s_andn2_b32 s27, s27, 63
	s_and_b32 s1, s1, 0x3fffff0
	s_sub_i32 s1, s26, s1
	v_or_b32_e32 v10, s27, v3
	s_lshl_b32 s1, s1, 6
	v_ashrrev_i32_e32 v11, 31, v10
	v_lshl_add_u64 v[14:15], v[10:11], 2, s[6:7]
	v_add_u32_e32 v10, s1, v4
	v_ashrrev_i32_e32 v11, 31, v10
	v_lshlrev_b64 v[10:11], 12, v[10:11]
	v_add_u32_e32 v16, s1, v7
	v_lshl_add_u64 v[10:11], v[14:15], 0, v[10:11]
	v_ashrrev_i32_e32 v17, 31, v16
	global_load_dwordx4 v[10:13], v[10:11], off nt
	v_lshlrev_b64 v[16:17], 12, v[16:17]
	v_lshl_add_u64 v[14:15], v[14:15], 0, v[16:17]
	global_load_dwordx4 v[14:17], v[14:15], off nt
	v_add_u32_e32 v18, 0xc300, v0
	v_add_u32_e32 v19, 0xc308, v0
	v_add_u32_e32 v20, 0xe380, v0
	v_add_u32_e32 v0, 0xe388, v0
	s_waitcnt vmcnt(1)
	ds_write2_b32 v18, v10, v11 offset1:1
	ds_write2_b32 v19, v12, v13 offset1:1
	s_waitcnt vmcnt(0)
	ds_write2_b32 v20, v14, v15 offset1:1
	ds_write2_b32 v0, v16, v17 offset1:1

.LBB0_471:
	s_ashr_i32 s1, s36, 31
	s_lshr_b32 s1, s1, 28
	s_add_i32 s1, s36, s1
	s_ashr_i32 s1, s1, 4
	s_lshl_b32 s37, s1, 6
	s_lshl_b32 s29, s1, 5
	s_and_b32 s28, s37, 64
	s_and_b32 s29, s29, 0xffffff80
	s_lshl_b32 s48, s1, 10
	s_or_b32 s28, s29, s28
	s_bitcmp0_b32 s1, 1
	v_or_b32_e32 v2, s28, v11
	s_cselect_b32 s1, s20, s23
	s_cselect_b32 s28, s0, s21
	v_mov_b32_e32 v4, s28
	v_mov_b32_e32 v5, s1
	v_ashrrev_i32_e32 v3, 31, v2
	s_sub_i32 s1, s34, s48
	v_lshl_add_u64 v[6:7], v[2:3], 2, v[4:5]
	v_add_u32_e32 v8, s1, v14
	v_mad_i64_i32 v[2:3], s[28:29], v8, s19, v[6:7]
	global_load_dwordx4 v[2:5], v[2:3], off nt
	v_ashrrev_i32_e32 v9, 31, v8
	v_cndmask_b32_e64 v0, 0, 1, s[8:9]
	v_cmp_ne_u32_e64 s[42:43], 1, v0
	s_andn2_b64 vcc, exec, s[8:9]
	v_lshl_add_u64 v[12:13], v[8:9], 2, s[24:25]
	s_cbranch_vccnz .LBB0_473
	global_load_dword v0, v[12:13], off
	s_waitcnt vmcnt(0)
	v_pk_mul_f32 v[4:5], v[4:5], v[0:1] op_sel_hi:[1,0]
	v_pk_mul_f32 v[2:3], v[2:3], v[0:1] op_sel_hi:[1,0]
.LBB0_473:
	v_add_u32_e32 v0, 32, v8
	v_mad_i64_i32 v[6:7], s[28:29], v0, s19, v[6:7]
	global_load_dwordx4 v[6:9], v[6:7], off nt
	s_mul_i32 s50, s30, 0x10400
	v_add_u32_e32 v0, s50, v18
	v_add_u32_e32 v0, v0, v16
	s_and_b64 vcc, exec, s[42:43]
	s_waitcnt vmcnt(1)
	ds_write2_b32 v0, v2, v3 offset1:1
	ds_write2_b32 v0, v4, v5 offset0:2 offset1:3
	s_cbranch_vccnz .LBB0_475
	global_load_dword v2, v[12:13], off offset:128
	s_waitcnt vmcnt(0)
	v_pk_mul_f32 v[8:9], v[8:9], v[2:3] op_sel_hi:[1,0]
	v_pk_mul_f32 v[6:7], v[6:7], v[2:3] op_sel_hi:[1,0]
.LBB0_475:
	s_add_i32 s49, s14, s36
	v_add_u32_e32 v2, 0x2080, v0
	s_cmpk_lt_i32 s49, 0x580
	s_waitcnt vmcnt(0)
	ds_write2_b32 v2, v6, v7 offset1:1
	v_add_u32_e32 v2, 0x2088, v0
	s_cselect_b64 s[28:29], -1, 0
	s_cmpk_gt_i32 s49, 0x57f
	ds_write2_b32 v2, v8, v9 offset1:1
	s_cbranch_scc1 .LBB0_491
	s_ashr_i32 s1, s49, 31
	s_lshr_b32 s1, s1, 28
	s_add_i32 s1, s49, s1
	s_ashr_i32 s33, s1, 4
	s_and_b32 s1, s1, 0x3fffff0
	s_lshl_b32 s52, s33, 6
	s_sub_i32 s1, s49, s1
	s_lshl_b32 s51, s1, 6
	s_and_b32 s1, s52, 64
	s_lshl_b32 s52, s33, 5
	s_and_b32 s52, s52, 0xffffff80
	s_or_b32 s1, s52, s1
	s_bitcmp0_b32 s33, 1
	v_or_b32_e32 v2, s1, v11
	s_cselect_b32 s1, s20, s23
	s_cselect_b32 s33, s0, s21
	v_mov_b32_e32 v4, s33
	v_mov_b32_e32 v5, s1
	v_ashrrev_i32_e32 v3, 31, v2
	v_lshl_add_u64 v[6:7], v[2:3], 2, v[4:5]
	v_add_u32_e32 v8, s51, v14
	v_mad_i64_i32 v[2:3], s[52:53], v8, s19, v[6:7]
	global_load_dwordx4 v[2:5], v[2:3], off nt
	v_ashrrev_i32_e32 v9, 31, v8
	s_and_b64 vcc, exec, s[42:43]
	v_lshl_add_u64 v[12:13], v[8:9], 2, s[24:25]
	s_cbranch_vccnz .LBB0_478
	global_load_dword v8, v[12:13], off
	s_waitcnt vmcnt(0)
	v_pk_mul_f32 v[4:5], v[4:5], v[8:9] op_sel_hi:[1,0]
	v_pk_mul_f32 v[2:3], v[2:3], v[8:9] op_sel_hi:[1,0]
.LBB0_478:
	v_add_u32_e32 v8, s51, v17
	v_mad_i64_i32 v[6:7], s[52:53], v8, s19, v[6:7]
	global_load_dwordx4 v[6:9], v[6:7], off nt
	v_add_u32_e32 v20, 0x4100, v0
	s_waitcnt vmcnt(1)
	ds_write2_b32 v20, v2, v3 offset1:1
	v_add_u32_e32 v2, 0x4108, v0
	s_and_b64 vcc, exec, s[42:43]
	ds_write2_b32 v2, v4, v5 offset1:1
	s_cbranch_vccnz .LBB0_480
	global_load_dword v2, v[12:13], off offset:128
	s_waitcnt vmcnt(0)
	v_pk_mul_f32 v[8:9], v[8:9], v[2:3] op_sel_hi:[1,0]
	v_pk_mul_f32 v[6:7], v[6:7], v[2:3] op_sel_hi:[1,0]
.LBB0_480:
	v_add_u32_e32 v2, 0x6180, v0
	s_add_i32 s51, s18, s36
	s_waitcnt vmcnt(0)
	ds_write2_b32 v2, v6, v7 offset1:1
	v_add_u32_e32 v2, 0x6188, v0
	s_cmpk_gt_i32 s51, 0x57f
	ds_write2_b32 v2, v8, v9 offset1:1
	s_cbranch_scc1 .LBB0_491
	s_ashr_i32 s1, s51, 31
	s_lshr_b32 s1, s1, 28
	s_add_i32 s1, s51, s1
	s_ashr_i32 s33, s1, 4
	s_and_b32 s1, s1, 0x3fffff0
	s_lshl_b32 s52, s33, 6
	s_sub_i32 s1, s51, s1
	s_lshl_b32 s51, s1, 6
	s_and_b32 s1, s52, 64
	s_lshl_b32 s52, s33, 5
	s_and_b32 s52, s52, 0xffffff80
	s_or_b32 s1, s52, s1
	s_bitcmp0_b32 s33, 1
	v_or_b32_e32 v2, s1, v11
	s_cselect_b32 s1, s20, s23
	s_cselect_b32 s33, s0, s21
	v_mov_b32_e32 v4, s33
	v_mov_b32_e32 v5, s1
	v_ashrrev_i32_e32 v3, 31, v2
	v_lshl_add_u64 v[6:7], v[2:3], 2, v[4:5]
	v_add_u32_e32 v8, s51, v14
	v_mad_i64_i32 v[2:3], s[52:53], v8, s19, v[6:7]
	global_load_dwordx4 v[2:5], v[2:3], off nt
	v_ashrrev_i32_e32 v9, 31, v8
	s_and_b64 vcc, exec, s[42:43]
	v_lshl_add_u64 v[12:13], v[8:9], 2, s[24:25]
	s_cbranch_vccnz .LBB0_483
	global_load_dword v8, v[12:13], off
	s_waitcnt vmcnt(0)
	v_pk_mul_f32 v[4:5], v[4:5], v[8:9] op_sel_hi:[1,0]
	v_pk_mul_f32 v[2:3], v[2:3], v[8:9] op_sel_hi:[1,0]
.LBB0_483:
	v_add_u32_e32 v8, s51, v17
	v_mad_i64_i32 v[6:7], s[52:53], v8, s19, v[6:7]
	global_load_dwordx4 v[6:9], v[6:7], off nt
	v_add_u32_e32 v20, 0x8200, v0
	s_waitcnt vmcnt(1)
	ds_write2_b32 v20, v2, v3 offset1:1
	v_add_u32_e32 v2, 0x8208, v0
	s_and_b64 vcc, exec, s[42:43]
	ds_write2_b32 v2, v4, v5 offset1:1
	s_cbranch_vccnz .LBB0_485
	global_load_dword v2, v[12:13], off offset:128
	s_waitcnt vmcnt(0)
	v_pk_mul_f32 v[8:9], v[8:9], v[2:3] op_sel_hi:[1,0]
	v_pk_mul_f32 v[6:7], v[6:7], v[2:3] op_sel_hi:[1,0]
.LBB0_485:
	v_add_u32_e32 v2, 0xa280, v0
	s_add_i32 s51, s15, s36
	s_waitcnt vmcnt(0)
	ds_write2_b32 v2, v6, v7 offset1:1
	v_add_u32_e32 v2, 0xa288, v0
	s_cmpk_gt_i32 s51, 0x57f
	ds_write2_b32 v2, v8, v9 offset1:1
	s_cbranch_scc1 .LBB0_491
	s_ashr_i32 s1, s51, 31
	s_lshr_b32 s1, s1, 28
	s_add_i32 s1, s51, s1
	s_ashr_i32 s33, s1, 4
	s_and_b32 s1, s1, 0x3fffff0
	s_lshl_b32 s52, s33, 6
	s_sub_i32 s1, s51, s1
	s_lshl_b32 s51, s1, 6
	s_and_b32 s1, s52, 64
	s_lshl_b32 s52, s33, 5
	s_and_b32 s52, s52, 0xffffff80
	s_or_b32 s1, s52, s1
	s_bitcmp0_b32 s33, 1
	v_or_b32_e32 v2, s1, v11
	s_cselect_b32 s1, s20, s23
	s_cselect_b32 s33, s0, s21
	v_mov_b32_e32 v4, s33
	v_mov_b32_e32 v5, s1
	v_ashrrev_i32_e32 v3, 31, v2
	v_lshl_add_u64 v[6:7], v[2:3], 2, v[4:5]
	v_add_u32_e32 v8, s51, v14
	v_mad_i64_i32 v[2:3], s[52:53], v8, s19, v[6:7]
	global_load_dwordx4 v[2:5], v[2:3], off nt
	v_ashrrev_i32_e32 v9, 31, v8
	s_and_b64 vcc, exec, s[42:43]
	v_lshl_add_u64 v[12:13], v[8:9], 2, s[24:25]
	s_cbranch_vccnz .LBB0_488
	global_load_dword v8, v[12:13], off
	s_waitcnt vmcnt(0)
	v_pk_mul_f32 v[4:5], v[4:5], v[8:9] op_sel_hi:[1,0]
	v_pk_mul_f32 v[2:3], v[2:3], v[8:9] op_sel_hi:[1,0]
.LBB0_488:
	v_add_u32_e32 v8, s51, v17
	v_mad_i64_i32 v[6:7], s[52:53], v8, s19, v[6:7]
	global_load_dwordx4 v[6:9], v[6:7], off nt
	v_add_u32_e32 v20, 0xc300, v0
	s_waitcnt vmcnt(1)
	ds_write2_b32 v20, v2, v3 offset1:1
	v_add_u32_e32 v2, 0xc308, v0
	s_and_b64 vcc, exec, s[42:43]
	ds_write2_b32 v2, v4, v5 offset1:1
	s_cbranch_vccnz .LBB0_490
	global_load_dword v2, v[12:13], off offset:128
	s_waitcnt vmcnt(0)
	v_pk_mul_f32 v[8:9], v[8:9], v[2:3] op_sel_hi:[1,0]
	v_pk_mul_f32 v[6:7], v[6:7], v[2:3] op_sel_hi:[1,0]

.LBB0_499:
	s_mul_hi_i32 s1, s34, 0x2e8ba2e9
	s_lshr_b32 s28, s1, 31
	s_ashr_i32 s1, s1, 3
	s_add_i32 s1, s1, s28
	s_lshl_b32 s29, s1, 6
	s_mulk_i32 s1, 0xf500
	s_add_i32 s28, s1, s21
	v_or_b32_e32 v10, s29, v2
	v_add_u32_e32 v16, s28, v3
	v_ashrrev_i32_e32 v11, 31, v10
	v_ashrrev_i32_e32 v17, 31, v16
	v_lshl_add_u64 v[14:15], v[10:11], 2, s[24:25]
	v_lshlrev_b64 v[10:11], 12, v[16:17]
	v_add_u32_e32 v16, 32, v16
	v_lshl_add_u64 v[10:11], v[14:15], 0, v[10:11]
	v_ashrrev_i32_e32 v17, 31, v16
	global_load_dwordx4 v[10:13], v[10:11], off nt
	v_lshlrev_b64 v[16:17], 12, v[16:17]
	v_lshl_add_u64 v[14:15], v[14:15], 0, v[16:17]
	global_load_dwordx4 v[14:17], v[14:15], off nt
	s_mul_i32 s42, s0, 0x10400
	s_add_i32 s36, s14, s34
	v_add_u32_e32 v9, s42, v7
	s_cmpk_lt_i32 s36, 0x2c0
	v_add_u32_e32 v9, v9, v5
	s_cselect_b64 s[30:31], -1, 0
	s_cmpk_gt_i32 s36, 0x2bf
	s_mul_hi_i32 s37, s36, 0x2e8ba2e9
	v_add_u32_e32 v18, 0x2080, v9
	v_add_u32_e32 v19, 0x2088, v9
	s_waitcnt vmcnt(1)
	ds_write2_b32 v9, v10, v11 offset1:1
	ds_write2_b32 v9, v12, v13 offset0:2 offset1:3
	s_waitcnt vmcnt(0)
	ds_write2_b32 v18, v14, v15 offset1:1
	ds_write2_b32 v19, v16, v17 offset1:1
	s_cbranch_scc1 .LBB0_503
	s_lshr_b32 s1, s37, 31
	s_ashr_i32 s33, s37, 3
	s_add_i32 s1, s33, s1
	s_mul_i32 s33, s1, 44
	s_sub_i32 s33, s36, s33
	v_lshl_or_b32 v10, s1, 6, v2
	s_lshl_b32 s33, s33, 6
	v_ashrrev_i32_e32 v11, 31, v10
	v_lshl_add_u64 v[14:15], v[10:11], 2, s[24:25]
	v_add_u32_e32 v10, s33, v3
	v_ashrrev_i32_e32 v11, 31, v10
	v_lshlrev_b64 v[10:11], 12, v[10:11]
	v_add_u32_e32 v16, s33, v6
	v_lshl_add_u64 v[10:11], v[14:15], 0, v[10:11]
	v_ashrrev_i32_e32 v17, 31, v16
	global_load_dwordx4 v[10:13], v[10:11], off nt
	v_lshlrev_b64 v[16:17], 12, v[16:17]
	v_lshl_add_u64 v[14:15], v[14:15], 0, v[16:17]
	global_load_dwordx4 v[14:17], v[14:15], off nt
	s_add_i32 s43, s18, s34
	v_add_u32_e32 v18, 0x4100, v9
	s_cmpk_gt_i32 s43, 0x2bf
	v_add_u32_e32 v19, 0x4108, v9
	v_add_u32_e32 v20, 0x6180, v9
	v_add_u32_e32 v21, 0x6188, v9
	s_waitcnt vmcnt(1)
	ds_write2_b32 v18, v10, v11 offset1:1
	ds_write2_b32 v19, v12, v13 offset1:1
	s_waitcnt vmcnt(0)
	ds_write2_b32 v20, v14, v15 offset1:1
	ds_write2_b32 v21, v16, v17 offset1:1
	s_cbranch_scc1 .LBB0_503
	s_mul_hi_i32 s1, s43, 0x2e8ba2e9
	s_lshr_b32 s33, s1, 31
	s_ashr_i32 s1, s1, 3
	s_add_i32 s1, s1, s33
	s_mul_i32 s33, s1, 44
	s_sub_i32 s33, s43, s33
	v_lshl_or_b32 v10, s1, 6, v2
	s_lshl_b32 s33, s33, 6
	v_ashrrev_i32_e32 v11, 31, v10
	v_lshl_add_u64 v[14:15], v[10:11], 2, s[24:25]
	v_add_u32_e32 v10, s33, v3
	v_ashrrev_i32_e32 v11, 31, v10
	v_lshlrev_b64 v[10:11], 12, v[10:11]
	v_add_u32_e32 v16, s33, v6
	v_lshl_add_u64 v[10:11], v[14:15], 0, v[10:11]
	v_ashrrev_i32_e32 v17, 31, v16
	global_load_dwordx4 v[10:13], v[10:11], off nt
	v_lshlrev_b64 v[16:17], 12, v[16:17]
	v_lshl_add_u64 v[14:15], v[14:15], 0, v[16:17]
	global_load_dwordx4 v[14:17], v[14:15], off nt
	s_add_i32 s43, s15, s34
	v_add_u32_e32 v18, 0x8200, v9
	s_cmpk_gt_i32 s43, 0x2bf
	v_add_u32_e32 v19, 0x8208, v9
	v_add_u32_e32 v20, 0xa280, v9
	v_add_u32_e32 v21, 0xa288, v9
	s_waitcnt vmcnt(1)
	ds_write2_b32 v18, v10, v11 offset1:1
	ds_write2_b32 v19, v12, v13 offset1:1
	s_waitcnt vmcnt(0)
	ds_write2_b32 v20, v14, v15 offset1:1
	ds_write2_b32 v21, v16, v17 offset1:1
	s_cbranch_scc1 .LBB0_503
	s_mul_hi_i32 s1, s43, 0x2e8ba2e9
	s_lshr_b32 s33, s1, 31
	s_ashr_i32 s1, s1, 3
	s_add_i32 s1, s1, s33
	s_mul_i32 s33, s1, 44
	s_sub_i32 s33, s43, s33
	v_lshl_or_b32 v10, s1, 6, v2
	s_lshl_b32 s33, s33, 6
	v_ashrrev_i32_e32 v11, 31, v10
	v_lshl_add_u64 v[14:15], v[10:11], 2, s[24:25]
	v_add_u32_e32 v10, s33, v3
	v_ashrrev_i32_e32 v11, 31, v10
	v_lshlrev_b64 v[10:11], 12, v[10:11]
	v_add_u32_e32 v16, s33, v6
	v_lshl_add_u64 v[10:11], v[14:15], 0, v[10:11]
	v_ashrrev_i32_e32 v17, 31, v16
	global_load_dwordx4 v[10:13], v[10:11], off nt
	v_lshlrev_b64 v[16:17], 12, v[16:17]
	v_lshl_add_u64 v[14:15], v[14:15], 0, v[16:17]
	global_load_dwordx4 v[14:17], v[14:15], off nt
	v_add_u32_e32 v18, 0xc300, v9
	v_add_u32_e32 v19, 0xc308, v9
	v_add_u32_e32 v20, 0xe380, v9
	v_add_u32_e32 v9, 0xe388, v9
	s_waitcnt vmcnt(1)
	ds_write2_b32 v18, v10, v11 offset1:1
	ds_write2_b32 v19, v12, v13 offset1:1
	s_waitcnt vmcnt(0)
	ds_write2_b32 v20, v14, v15 offset1:1
	ds_write2_b32 v9, v16, v17 offset1:1

.LBB0_510:
	s_ashr_i32 s1, s21, 31
	s_lshr_b32 s1, s1, 28
	s_add_i32 s1, s21, s1
	s_ashr_i32 s1, s1, 4
	s_lshl_b32 s48, s1, 10
	s_lshl_b32 s34, s1, 6
	s_sub_i32 s1, s20, s48
	v_or_b32_e32 v2, s34, v11
	v_add_u32_e32 v8, s1, v14
	v_ashrrev_i32_e32 v3, 31, v2
	v_ashrrev_i32_e32 v9, 31, v8
	v_lshl_add_u64 v[6:7], v[2:3], 2, s[24:25]
	v_lshlrev_b64 v[2:3], 12, v[8:9]
	v_lshl_add_u64 v[2:3], v[6:7], 0, v[2:3]
	global_load_dwordx4 v[2:5], v[2:3], off nt
	v_cndmask_b32_e64 v0, 0, 1, s[30:31]
	v_cmp_ne_u32_e64 s[42:43], 1, v0
	s_andn2_b64 vcc, exec, s[30:31]
	v_lshl_add_u64 v[12:13], v[8:9], 2, s[26:27]
	s_cbranch_vccnz .LBB0_512
	global_load_dword v0, v[12:13], off
	s_waitcnt vmcnt(0)
	v_pk_mul_f32 v[4:5], v[4:5], v[0:1] op_sel_hi:[1,0]
	v_pk_mul_f32 v[2:3], v[2:3], v[0:1] op_sel_hi:[1,0]
.LBB0_512:
	v_add_u32_e32 v8, 32, v8
	v_ashrrev_i32_e32 v9, 31, v8
	v_lshlrev_b64 v[8:9], 12, v[8:9]
	v_lshl_add_u64 v[6:7], v[6:7], 0, v[8:9]
	global_load_dwordx4 v[6:9], v[6:7], off nt
	s_mul_i32 s50, s0, 0x10400
	v_add_u32_e32 v0, s50, v18
	v_add_u32_e32 v0, v0, v16
	s_and_b64 vcc, exec, s[42:43]
	s_waitcnt vmcnt(1)
	ds_write2_b32 v0, v2, v3 offset1:1
	ds_write2_b32 v0, v4, v5 offset0:2 offset1:3
	s_cbranch_vccnz .LBB0_514
	global_load_dword v2, v[12:13], off offset:128
	s_waitcnt vmcnt(0)
	v_pk_mul_f32 v[8:9], v[8:9], v[2:3] op_sel_hi:[1,0]
	v_pk_mul_f32 v[6:7], v[6:7], v[2:3] op_sel_hi:[1,0]
.LBB0_514:
	s_add_i32 s49, s14, s21
	v_add_u32_e32 v2, 0x2080, v0
	s_cmpk_lt_i32 s49, 0x100
	s_waitcnt vmcnt(0)
	ds_write2_b32 v2, v6, v7 offset1:1
	v_add_u32_e32 v2, 0x2088, v0
	s_cselect_b64 s[36:37], -1, 0
	s_cmpk_gt_i32 s49, 0xff
	ds_write2_b32 v2, v8, v9 offset1:1
	s_cbranch_scc1 .LBB0_530
	s_ashr_i32 s1, s49, 31
	s_lshr_b32 s1, s1, 28
	s_add_i32 s1, s49, s1
	s_lshl_b32 s33, s1, 2
	s_and_b32 s1, s1, 0x3fffff0
	s_sub_i32 s1, s49, s1
	s_andn2_b32 s33, s33, 63
	s_lshl_b32 s51, s1, 6
	v_or_b32_e32 v2, s33, v11
	v_add_u32_e32 v8, s51, v14
	v_ashrrev_i32_e32 v3, 31, v2
	v_ashrrev_i32_e32 v9, 31, v8
	v_lshl_add_u64 v[6:7], v[2:3], 2, s[24:25]
	v_lshlrev_b64 v[2:3], 12, v[8:9]
	v_lshl_add_u64 v[2:3], v[6:7], 0, v[2:3]
	global_load_dwordx4 v[2:5], v[2:3], off nt
	s_and_b64 vcc, exec, s[42:43]
	v_lshl_add_u64 v[12:13], v[8:9], 2, s[26:27]
	s_cbranch_vccnz .LBB0_517
	global_load_dword v8, v[12:13], off
	s_waitcnt vmcnt(0)
	v_pk_mul_f32 v[4:5], v[4:5], v[8:9] op_sel_hi:[1,0]
	v_pk_mul_f32 v[2:3], v[2:3], v[8:9] op_sel_hi:[1,0]
.LBB0_517:
	v_add_u32_e32 v8, s51, v17
	v_ashrrev_i32_e32 v9, 31, v8
	v_lshlrev_b64 v[8:9], 12, v[8:9]
	v_lshl_add_u64 v[6:7], v[6:7], 0, v[8:9]
	global_load_dwordx4 v[6:9], v[6:7], off nt
	v_add_u32_e32 v20, 0x4100, v0
	s_waitcnt vmcnt(1)
	ds_write2_b32 v20, v2, v3 offset1:1
	v_add_u32_e32 v2, 0x4108, v0
	s_and_b64 vcc, exec, s[42:43]
	ds_write2_b32 v2, v4, v5 offset1:1
	s_cbranch_vccnz .LBB0_519
	global_load_dword v2, v[12:13], off offset:128
	s_waitcnt vmcnt(0)
	v_pk_mul_f32 v[8:9], v[8:9], v[2:3] op_sel_hi:[1,0]
	v_pk_mul_f32 v[6:7], v[6:7], v[2:3] op_sel_hi:[1,0]
.LBB0_519:
	v_add_u32_e32 v2, 0x6180, v0
	s_add_i32 s51, s18, s21
	s_waitcnt vmcnt(0)
	ds_write2_b32 v2, v6, v7 offset1:1
	v_add_u32_e32 v2, 0x6188, v0
	s_cmpk_gt_i32 s51, 0xff
	ds_write2_b32 v2, v8, v9 offset1:1
	s_cbranch_scc1 .LBB0_530
	s_ashr_i32 s1, s51, 31
	s_lshr_b32 s1, s1, 28
	s_add_i32 s1, s51, s1
	s_lshl_b32 s33, s1, 2
	s_and_b32 s1, s1, 0x3fffff0
	s_sub_i32 s1, s51, s1
	s_andn2_b32 s33, s33, 63
	s_lshl_b32 s51, s1, 6
	v_or_b32_e32 v2, s33, v11
	v_add_u32_e32 v8, s51, v14
	v_ashrrev_i32_e32 v3, 31, v2
	v_ashrrev_i32_e32 v9, 31, v8
	v_lshl_add_u64 v[6:7], v[2:3], 2, s[24:25]
	v_lshlrev_b64 v[2:3], 12, v[8:9]
	v_lshl_add_u64 v[2:3], v[6:7], 0, v[2:3]
	global_load_dwordx4 v[2:5], v[2:3], off nt
	s_and_b64 vcc, exec, s[42:43]
	v_lshl_add_u64 v[12:13], v[8:9], 2, s[26:27]
	s_cbranch_vccnz .LBB0_522
	global_load_dword v8, v[12:13], off
	s_waitcnt vmcnt(0)
	v_pk_mul_f32 v[4:5], v[4:5], v[8:9] op_sel_hi:[1,0]
	v_pk_mul_f32 v[2:3], v[2:3], v[8:9] op_sel_hi:[1,0]
.LBB0_522:
	v_add_u32_e32 v8, s51, v17
	v_ashrrev_i32_e32 v9, 31, v8
	v_lshlrev_b64 v[8:9], 12, v[8:9]
	v_lshl_add_u64 v[6:7], v[6:7], 0, v[8:9]
	global_load_dwordx4 v[6:9], v[6:7], off nt
	v_add_u32_e32 v20, 0x8200, v0
	s_waitcnt vmcnt(1)
	ds_write2_b32 v20, v2, v3 offset1:1
	v_add_u32_e32 v2, 0x8208, v0
	s_and_b64 vcc, exec, s[42:43]
	ds_write2_b32 v2, v4, v5 offset1:1
	s_cbranch_vccnz .LBB0_524
	global_load_dword v2, v[12:13], off offset:128
	s_waitcnt vmcnt(0)
	v_pk_mul_f32 v[8:9], v[8:9], v[2:3] op_sel_hi:[1,0]
	v_pk_mul_f32 v[6:7], v[6:7], v[2:3] op_sel_hi:[1,0]
.LBB0_524:
	v_add_u32_e32 v2, 0xa280, v0
	s_add_i32 s51, s15, s21
	s_waitcnt vmcnt(0)
	ds_write2_b32 v2, v6, v7 offset1:1
	v_add_u32_e32 v2, 0xa288, v0
	s_cmpk_gt_i32 s51, 0xff
	ds_write2_b32 v2, v8, v9 offset1:1
	s_cbranch_scc1 .LBB0_530
	s_ashr_i32 s1, s51, 31
	s_lshr_b32 s1, s1, 28
	s_add_i32 s1, s51, s1
	s_lshl_b32 s33, s1, 2
	s_and_b32 s1, s1, 0x3fffff0
	s_sub_i32 s1, s51, s1
	s_andn2_b32 s33, s33, 63
	s_lshl_b32 s51, s1, 6
	v_or_b32_e32 v2, s33, v11
	v_add_u32_e32 v8, s51, v14
	v_ashrrev_i32_e32 v3, 31, v2
	v_ashrrev_i32_e32 v9, 31, v8
	v_lshl_add_u64 v[6:7], v[2:3], 2, s[24:25]
	v_lshlrev_b64 v[2:3], 12, v[8:9]
	v_lshl_add_u64 v[2:3], v[6:7], 0, v[2:3]
	global_load_dwordx4 v[2:5], v[2:3], off nt
	s_and_b64 vcc, exec, s[42:43]
	v_lshl_add_u64 v[12:13], v[8:9], 2, s[26:27]
	s_cbranch_vccnz .LBB0_527
	global_load_dword v8, v[12:13], off
	s_waitcnt vmcnt(0)
	v_pk_mul_f32 v[4:5], v[4:5], v[8:9] op_sel_hi:[1,0]
	v_pk_mul_f32 v[2:3], v[2:3], v[8:9] op_sel_hi:[1,0]
.LBB0_527:
	v_add_u32_e32 v8, s51, v17
	v_ashrrev_i32_e32 v9, 31, v8
	v_lshlrev_b64 v[8:9], 12, v[8:9]
	v_lshl_add_u64 v[6:7], v[6:7], 0, v[8:9]
	global_load_dwordx4 v[6:9], v[6:7], off nt
	v_add_u32_e32 v20, 0xc300, v0
	s_waitcnt vmcnt(1)
	ds_write2_b32 v20, v2, v3 offset1:1
	v_add_u32_e32 v2, 0xc308, v0
	s_and_b64 vcc, exec, s[42:43]
	ds_write2_b32 v2, v4, v5 offset1:1
	s_cbranch_vccnz .LBB0_529
	global_load_dword v2, v[12:13], off offset:128
	s_waitcnt vmcnt(0)
	v_pk_mul_f32 v[8:9], v[8:9], v[2:3] op_sel_hi:[1,0]
	v_pk_mul_f32 v[6:7], v[6:7], v[2:3] op_sel_hi:[1,0]

.LBB0_538:
	s_ashr_i32 s1, s21, 31
	s_lshr_b32 s1, s1, 30
	s_add_i32 s1, s21, s1
	s_ashr_i32 s1, s1, 2
	s_lshl_b32 s30, s1, 8
	s_lshl_b32 s28, s1, 6
	s_sub_i32 s1, s20, s30
	v_or_b32_e32 v10, s28, v3
	v_add_u32_e32 v16, s1, v4
	v_ashrrev_i32_e32 v11, 31, v10
	v_ashrrev_i32_e32 v17, 31, v16
	v_lshl_add_u64 v[14:15], v[10:11], 2, s[22:23]
	v_lshlrev_b64 v[10:11], 12, v[16:17]
	v_add_u32_e32 v16, 32, v16
	v_lshl_add_u64 v[10:11], v[14:15], 0, v[10:11]
	v_ashrrev_i32_e32 v17, 31, v16
	global_load_dwordx4 v[10:13], v[10:11], off nt
	v_lshlrev_b64 v[16:17], 12, v[16:17]
	v_lshl_add_u64 v[14:15], v[14:15], 0, v[16:17]
	global_load_dwordx4 v[14:17], v[14:15], off nt
	s_mul_i32 s31, s0, 0x10400
	s_add_i32 s29, s14, s21
	v_add_u32_e32 v0, s31, v8
	s_cmp_lt_i32 s29, 64
	v_add_u32_e32 v0, v0, v6
	s_cselect_b64 s[26:27], -1, 0
	s_cmp_gt_i32 s29, 63
	v_add_u32_e32 v18, 0x2080, v0
	v_add_u32_e32 v19, 0x2088, v0
	s_waitcnt vmcnt(1)
	ds_write2_b32 v0, v10, v11 offset1:1
	ds_write2_b32 v0, v12, v13 offset0:2 offset1:3
	s_waitcnt vmcnt(0)
	ds_write2_b32 v18, v14, v15 offset1:1
	ds_write2_b32 v19, v16, v17 offset1:1
	s_cbranch_scc1 .LBB0_542
	s_ashr_i32 s1, s29, 31
	s_lshr_b32 s1, s1, 30
	s_add_i32 s1, s29, s1
	s_lshl_b32 s33, s1, 4
	s_andn2_b32 s33, s33, 63
	s_and_b32 s1, s1, 0x3fffffc
	s_sub_i32 s1, s29, s1
	v_or_b32_e32 v10, s33, v3
	s_lshl_b32 s1, s1, 6
	v_ashrrev_i32_e32 v11, 31, v10
	v_lshl_add_u64 v[14:15], v[10:11], 2, s[22:23]
	v_add_u32_e32 v10, s1, v4
	v_ashrrev_i32_e32 v11, 31, v10
	v_lshlrev_b64 v[10:11], 12, v[10:11]
	v_add_u32_e32 v16, s1, v7
	v_lshl_add_u64 v[10:11], v[14:15], 0, v[10:11]
	v_ashrrev_i32_e32 v17, 31, v16
	global_load_dwordx4 v[10:13], v[10:11], off nt
	v_lshlrev_b64 v[16:17], 12, v[16:17]
	v_lshl_add_u64 v[14:15], v[14:15], 0, v[16:17]
	global_load_dwordx4 v[14:17], v[14:15], off nt
	s_add_i32 s34, s18, s21
	v_add_u32_e32 v18, 0x4100, v0
	s_cmp_gt_i32 s34, 63
	v_add_u32_e32 v19, 0x4108, v0
	v_add_u32_e32 v20, 0x6180, v0
	v_add_u32_e32 v21, 0x6188, v0
	s_waitcnt vmcnt(1)
	ds_write2_b32 v18, v10, v11 offset1:1
	ds_write2_b32 v19, v12, v13 offset1:1
	s_waitcnt vmcnt(0)
	ds_write2_b32 v20, v14, v15 offset1:1
	ds_write2_b32 v21, v16, v17 offset1:1
	s_cbranch_scc1 .LBB0_542
	s_ashr_i32 s1, s34, 31
	s_lshr_b32 s1, s1, 30
	s_add_i32 s1, s34, s1
	s_lshl_b32 s33, s1, 4
	s_andn2_b32 s33, s33, 63
	s_and_b32 s1, s1, 0x3fffffc
	s_sub_i32 s1, s34, s1
	v_or_b32_e32 v10, s33, v3
	s_lshl_b32 s1, s1, 6
	v_ashrrev_i32_e32 v11, 31, v10
	v_lshl_add_u64 v[14:15], v[10:11], 2, s[22:23]
	v_add_u32_e32 v10, s1, v4
	v_ashrrev_i32_e32 v11, 31, v10
	v_lshlrev_b64 v[10:11], 12, v[10:11]
	v_add_u32_e32 v16, s1, v7
	v_lshl_add_u64 v[10:11], v[14:15], 0, v[10:11]
	v_ashrrev_i32_e32 v17, 31, v16
	global_load_dwordx4 v[10:13], v[10:11], off nt
	v_lshlrev_b64 v[16:17], 12, v[16:17]
	v_lshl_add_u64 v[14:15], v[14:15], 0, v[16:17]
	global_load_dwordx4 v[14:17], v[14:15], off nt
	s_add_i32 s34, s15, s21
	v_add_u32_e32 v18, 0x8200, v0
	s_cmp_gt_i32 s34, 63
	v_add_u32_e32 v19, 0x8208, v0
	v_add_u32_e32 v20, 0xa280, v0
	v_add_u32_e32 v21, 0xa288, v0
	s_waitcnt vmcnt(1)
	ds_write2_b32 v18, v10, v11 offset1:1
	ds_write2_b32 v19, v12, v13 offset1:1
	s_waitcnt vmcnt(0)
	ds_write2_b32 v20, v14, v15 offset1:1
	ds_write2_b32 v21, v16, v17 offset1:1
	s_cbranch_scc1 .LBB0_542
	s_ashr_i32 s1, s34, 31
	s_lshr_b32 s1, s1, 30
	s_add_i32 s1, s34, s1
	s_lshl_b32 s33, s1, 4
	s_andn2_b32 s33, s33, 63
	s_and_b32 s1, s1, 0x3fffffc
	s_sub_i32 s1, s34, s1
	v_or_b32_e32 v10, s33, v3
	s_lshl_b32 s1, s1, 6
	v_ashrrev_i32_e32 v11, 31, v10
	v_lshl_add_u64 v[14:15], v[10:11], 2, s[22:23]
	v_add_u32_e32 v10, s1, v4
	v_ashrrev_i32_e32 v11, 31, v10
	v_lshlrev_b64 v[10:11], 12, v[10:11]
	v_add_u32_e32 v16, s1, v7
	v_lshl_add_u64 v[10:11], v[14:15], 0, v[10:11]
	v_ashrrev_i32_e32 v17, 31, v16
	global_load_dwordx4 v[10:13], v[10:11], off nt
	v_lshlrev_b64 v[16:17], 12, v[16:17]
	v_lshl_add_u64 v[14:15], v[14:15], 0, v[16:17]
	global_load_dwordx4 v[14:17], v[14:15], off nt
	v_add_u32_e32 v18, 0xc300, v0
	v_add_u32_e32 v19, 0xc308, v0
	v_add_u32_e32 v20, 0xe380, v0
	v_add_u32_e32 v0, 0xe388, v0
	s_waitcnt vmcnt(1)
	ds_write2_b32 v18, v10, v11 offset1:1
	ds_write2_b32 v19, v12, v13 offset1:1
	s_waitcnt vmcnt(0)
	ds_write2_b32 v20, v14, v15 offset1:1
	ds_write2_b32 v0, v16, v17 offset1:1

.LBB0_549:
	v_ashrrev_i32_e32 v53, 31, v52
	v_lshlrev_b64 v[2:3], 12, v[52:53]
	v_lshl_add_u64 v[10:11], v[56:57], 0, v[2:3]
	global_load_dwordx4 v[2:5], v[10:11], off nt
	s_waitcnt lgkmcnt(0)
	global_load_dwordx4 v[6:9], v[10:11], off offset:16 nt
	global_load_dwordx4 v[72:75], v[10:11], off offset:2048 nt
	global_load_dwordx4 v[76:79], v[10:11], off offset:2064 nt
	v_add_u32_e32 v64, 1, v52
	v_add_u32_e32 v62, 2, v52
	v_ashrrev_i32_e32 v65, 31, v64
	v_ashrrev_i32_e32 v63, 31, v62
	v_lshlrev_b64 v[10:11], 11, v[52:53]
	v_lshlrev_b64 v[12:13], 12, v[64:65]
	v_lshlrev_b64 v[14:15], 12, v[62:63]
	v_lshl_add_u64 v[84:85], v[58:59], 0, v[10:11]
	v_lshl_add_u64 v[10:11], v[56:57], 0, v[12:13]
	v_add_u32_e32 v60, 3, v52
	v_lshl_add_u64 v[12:13], v[56:57], 0, v[14:15]
	global_load_dwordx4 v[42:45], v[10:11], off offset:16 nt
	global_load_dwordx4 v[46:49], v[10:11], off nt
	global_load_dwordx4 v[34:37], v[10:11], off offset:2064 nt
	global_load_dwordx4 v[38:41], v[10:11], off offset:2048 nt
	global_load_dwordx4 v[26:29], v[12:13], off offset:16 nt
	global_load_dwordx4 v[30:33], v[12:13], off nt
	global_load_dwordx4 v[18:21], v[12:13], off offset:2064 nt
	global_load_dwordx4 v[22:25], v[12:13], off offset:2048 nt
	v_ashrrev_i32_e32 v61, 31, v60
	v_lshlrev_b64 v[16:17], 12, v[60:61]
	v_lshl_add_u64 v[86:87], v[56:57], 0, v[16:17]
	s_waitcnt vmcnt(11)
	v_mul_f32_e32 v0, v3, v3
	v_mul_f32_e32 v71, v5, v5
	s_waitcnt vmcnt(10)
	v_mul_f32_e32 v88, v7, v7
	v_mul_f32_e32 v89, v9, v9
	v_cvt_pk_bf16_f32 v80, v2, v3
	v_cvt_pk_bf16_f32 v81, v4, v5
	v_fmac_f32_e32 v0, v2, v2
	v_fmac_f32_e32 v71, v4, v4
	v_cvt_pk_bf16_f32 v82, v6, v7
	v_cvt_pk_bf16_f32 v83, v8, v9
	v_fmac_f32_e32 v88, v6, v6
	v_fmac_f32_e32 v89, v8, v8
	global_load_dwordx4 v[10:13], v[86:87], off offset:16 nt
	global_load_dwordx4 v[14:17], v[86:87], off nt
	global_load_dwordx4 v[2:5], v[86:87], off offset:2064 nt
	global_load_dwordx4 v[6:9], v[86:87], off offset:2048 nt
	v_add_f32_e32 v0, v0, v71
	global_store_dwordx4 v[84:85], v[80:83], off
	v_add_f32_e32 v71, v88, v89
	v_add_f32_e32 v0, v0, v71
	s_waitcnt vmcnt(14)
	v_cvt_pk_bf16_f32 v80, v72, v73
	v_mul_f32_e32 v73, v73, v73
	v_fmac_f32_e32 v73, v72, v72
	v_mul_f32_e32 v72, v75, v75
	v_cvt_pk_bf16_f32 v81, v74, v75
	v_fmac_f32_e32 v72, v74, v74
	s_waitcnt vmcnt(13)
	v_mul_f32_e32 v74, v77, v77
	v_mul_f32_e32 v75, v79, v79
	v_fmac_f32_e32 v74, v76, v76
	v_fmac_f32_e32 v75, v78, v78
	v_add_f32_e32 v72, v73, v72
	v_add_f32_e32 v73, v74, v75
	v_add_f32_e32 v71, v72, v73
	v_add_f32_e32 v0, v0, v71
	ds_bpermute_b32 v71, v51, v0
	v_cvt_pk_bf16_f32 v82, v76, v77
	v_cvt_pk_bf16_f32 v83, v78, v79
	global_store_dwordx4 v[84:85], v[80:83], off offset:1024
	s_waitcnt lgkmcnt(0)
	v_add_f32_e32 v0, v0, v71
	ds_bpermute_b32 v71, v66, v0
	s_waitcnt lgkmcnt(0)
	v_add_f32_e32 v0, v0, v71
	ds_bpermute_b32 v71, v67, v0
	s_waitcnt lgkmcnt(0)
	v_add_f32_e32 v0, v0, v71
	ds_bpermute_b32 v71, v68, v0
	s_waitcnt lgkmcnt(0)
	v_add_f32_e32 v0, v0, v71
	ds_bpermute_b32 v71, v69, v0
	s_waitcnt lgkmcnt(0)
	v_add_f32_e32 v0, v0, v71
	ds_bpermute_b32 v71, v70, v0
	s_and_saveexec_b64 s[22:23], vcc
	s_cbranch_execz .LBB0_551
	s_waitcnt lgkmcnt(0)
	v_add_f32_e32 v0, v0, v71
	v_lshlrev_b64 v[72:73], 6, v[52:53]
	v_cndmask_b32_e64 v0, 0, v0, s[40:41]
	v_lshl_add_u64 v[72:73], v[54:55], 0, v[72:73]
	global_store_dword v[72:73], v0, off

.LBB0_560:
	v_lshl_add_u64 v[30:31], s[46:47], 0, v[36:37]
	global_load_dwordx4 v[26:29], v[30:31], off offset:16 nt
	s_nop 0
	global_load_dwordx4 v[30:33], v[30:31], off nt
	v_lshl_add_u64 v[54:55], v[52:53], 0, s[16:17]
	s_mov_b64 s[0:1], 0x200000
	v_cmp_gt_u64_e32 vcc, s[0:1], v[54:55]
	s_and_saveexec_b64 s[36:37], vcc
	s_cbranch_execz .LBB0_562
	v_lshl_add_u64 v[22:23], s[46:47], 0, v[48:49]
	global_load_dwordx4 v[14:17], v[22:23], off nt
	s_nop 0
	global_load_dwordx4 v[22:25], v[22:23], off offset:-16 nt
.LBB0_562:
	s_or_b64 exec, exec, s[36:37]
	v_lshl_add_u64 v[56:57], s[24:25], 0, v[52:53]
	v_cmp_gt_u64_e64 s[40:41], s[0:1], v[56:57]
	s_and_saveexec_b64 s[36:37], s[40:41]
	s_cbranch_execz .LBB0_564
	v_lshl_add_u64 v[18:19], s[46:47], 0, v[38:39]
	global_load_dwordx4 v[6:9], v[18:19], off nt
	s_nop 0
	global_load_dwordx4 v[18:21], v[18:19], off offset:-16 nt
.LBB0_564:
	s_or_b64 exec, exec, s[36:37]
	v_lshl_add_u64 v[52:53], s[28:29], 0, v[52:53]
	v_cmp_gt_u64_e64 s[42:43], s[0:1], v[52:53]
	s_and_saveexec_b64 s[36:37], s[42:43]
	s_cbranch_execz .LBB0_566
	v_lshl_add_u64 v[10:11], s[46:47], 0, v[42:43]
	global_load_dwordx4 v[2:5], v[10:11], off nt
	s_nop 0
	global_load_dwordx4 v[10:13], v[10:11], off offset:-16 nt
